# GEMM K-loop: LDS-DMA window of the second wave half starts at MFMA slot 12 instead of 16 (first half stays at 8)
# speedup vs baseline: 1.0153x; 1.0153x over previous
; DI void lds_barrier() { asm volatile("s_waitcnt lgkmcnt(0)\n\ts_barrier" ::: "memory"); }
; #define G_LOAD(RA, RB, KT) { size_t as_ = astep, bs_ = bstep; asm volatile("" : "+s"(as_), "+s"(bs_)); \
;       _Pragma("unroll") for (int i = 0; i < 4; ++i) { RA[i] = *(const u32x4*)(Ag + i * as_ + (KT) * 64); RB[i] = *(const u32x4*)(Bg + i * bs_ + (KT) * 64); } }
; DI void gemm_run(const GemmCfg c, char* smem, float* const g_h, u16* const g_hb, float* const g_out, const int final_out) {
;     ...
;     G_LOAD(ra0, rb0, 0);
;     __syncthreads();
;     G_STORE(ra0, rb0, 0);
;     G_LOAD(ra0, rb0, 1);
;     lds_barrier();
;     int kt = 0;
;     for (; kt + 3 < nk; kt += 2) {
;       K_STEP(0, 1, kt + 2, true, true);
;       lds_barrier();
;       K_STEP(1, 0, kt + 3, true, true);
;       lds_barrier();
;     }
.Lgemm_kloop_nl:
	s_waitcnt lgkmcnt(8)
	v_mfma_f32_16x16x32_bf16 v[64:67], v[160:163], v[204:207], v[64:67]
	s_waitcnt lgkmcnt(7)
	v_mfma_f32_16x16x32_bf16 v[68:71], v[160:163], v[222:225], v[68:71]
	s_waitcnt lgkmcnt(6)
	v_mfma_f32_16x16x32_bf16 v[72:75], v[160:163], v[226:229], v[72:75]
	s_waitcnt lgkmcnt(5)
	v_mfma_f32_16x16x32_bf16 v[76:79], v[160:163], v[230:233], v[76:79]
	s_waitcnt lgkmcnt(4)
	v_mfma_f32_16x16x32_bf16 v[80:83], v[160:163], v[234:237], v[80:83]
	s_waitcnt lgkmcnt(3)
	v_mfma_f32_16x16x32_bf16 v[84:87], v[160:163], v[238:241], v[84:87]
	s_waitcnt lgkmcnt(2)
	v_mfma_f32_16x16x32_bf16 v[88:91], v[160:163], v[242:245], v[88:91]
	s_waitcnt lgkmcnt(1)
	v_mfma_f32_16x16x32_bf16 v[92:95], v[160:163], v[246:249], v[92:95]
	ds_read_b128 v[160:163], v215
	v_mfma_f32_16x16x32_bf16 v[96:99], v[176:179], v[204:207], v[96:99]
	v_mfma_f32_16x16x32_bf16 v[100:103], v[176:179], v[222:225], v[100:103]
	v_mfma_f32_16x16x32_bf16 v[104:107], v[176:179], v[226:229], v[104:107]
	v_mfma_f32_16x16x32_bf16 v[108:111], v[176:179], v[230:233], v[108:111]
	v_mfma_f32_16x16x32_bf16 v[112:115], v[176:179], v[234:237], v[112:115]
	v_mfma_f32_16x16x32_bf16 v[116:119], v[176:179], v[238:241], v[116:119]
	v_mfma_f32_16x16x32_bf16 v[120:123], v[176:179], v[242:245], v[120:123]
	v_mfma_f32_16x16x32_bf16 v[124:127], v[176:179], v[246:249], v[124:127]
	ds_read_b128 v[176:179], v215 offset:2048
	v_mfma_f32_16x16x32_bf16 v[0:3], v[180:183], v[204:207], v[0:3]
	v_mfma_f32_16x16x32_bf16 v[4:7], v[180:183], v[222:225], v[4:7]
	v_mfma_f32_16x16x32_bf16 v[8:11], v[180:183], v[226:229], v[8:11]
	v_mfma_f32_16x16x32_bf16 v[12:15], v[180:183], v[230:233], v[12:15]
	v_mfma_f32_16x16x32_bf16 v[16:19], v[180:183], v[234:237], v[16:19]
	v_mfma_f32_16x16x32_bf16 v[20:23], v[180:183], v[238:241], v[20:23]
	v_mfma_f32_16x16x32_bf16 v[24:27], v[180:183], v[242:245], v[24:27]
	v_mfma_f32_16x16x32_bf16 v[28:31], v[180:183], v[246:249], v[28:31]
	ds_read_b128 v[180:183], v215 offset:4096
	s_waitcnt lgkmcnt(3)
	v_mfma_f32_16x16x32_bf16 v[32:35], v[200:203], v[204:207], v[32:35]
	ds_read_b128 v[204:207], v197
	v_mfma_f32_16x16x32_bf16 v[36:39], v[200:203], v[222:225], v[36:39]
	ds_read_b128 v[222:225], v197 offset:2048
	v_mfma_f32_16x16x32_bf16 v[40:43], v[200:203], v[226:229], v[40:43]
	ds_read_b128 v[226:229], v197 offset:4096
	v_mfma_f32_16x16x32_bf16 v[44:47], v[200:203], v[230:233], v[44:47]
	ds_read_b128 v[230:233], v197 offset:6144
	v_mfma_f32_16x16x32_bf16 v[48:51], v[200:203], v[234:237], v[48:51]
	ds_read_b128 v[234:237], v197 offset:8192
	v_mfma_f32_16x16x32_bf16 v[52:55], v[200:203], v[238:241], v[52:55]
	ds_read_b128 v[238:241], v197 offset:10240
	v_mfma_f32_16x16x32_bf16 v[56:59], v[200:203], v[242:245], v[56:59]
	ds_read_b128 v[242:245], v197 offset:12288
	v_mfma_f32_16x16x32_bf16 v[60:63], v[200:203], v[246:249], v[60:63]
	ds_read_b128 v[246:249], v197 offset:14336
	ds_read_b128 v[200:203], v215 offset:6144
	s_waitcnt lgkmcnt(8)
	v_mfma_f32_16x16x32_bf16 v[64:67], v[160:163], v[204:207], v[64:67]
	s_waitcnt lgkmcnt(7)
	v_mfma_f32_16x16x32_bf16 v[68:71], v[160:163], v[222:225], v[68:71]
	s_waitcnt lgkmcnt(6)
	v_mfma_f32_16x16x32_bf16 v[72:75], v[160:163], v[226:229], v[72:75]
	s_waitcnt lgkmcnt(5)
	v_mfma_f32_16x16x32_bf16 v[76:79], v[160:163], v[230:233], v[76:79]
	s_waitcnt lgkmcnt(4)
	v_mfma_f32_16x16x32_bf16 v[80:83], v[160:163], v[234:237], v[80:83]
	s_waitcnt lgkmcnt(3)
	v_mfma_f32_16x16x32_bf16 v[84:87], v[160:163], v[238:241], v[84:87]
	s_waitcnt lgkmcnt(2)
	v_mfma_f32_16x16x32_bf16 v[88:91], v[160:163], v[242:245], v[88:91]
	s_waitcnt lgkmcnt(1)
	v_mfma_f32_16x16x32_bf16 v[92:95], v[160:163], v[246:249], v[92:95]
	s_waitcnt vmcnt(0) lgkmcnt(0)
	s_barrier
	ds_read_b128 v[160:163], v194 offset:36864
	v_mfma_f32_16x16x32_bf16 v[96:99], v[176:179], v[204:207], v[96:99]
	v_mfma_f32_16x16x32_bf16 v[100:103], v[176:179], v[222:225], v[100:103]
	v_mfma_f32_16x16x32_bf16 v[104:107], v[176:179], v[226:229], v[104:107]
	v_mfma_f32_16x16x32_bf16 v[108:111], v[176:179], v[230:233], v[108:111]
	s_add_u32 m0, s8, 0x0
	v_mfma_f32_16x16x32_bf16 v[112:115], v[176:179], v[234:237], v[112:115]
	global_load_lds_dwordx4 v130, s[4:5]
	s_add_u32 m0, s8, 0x12000
	v_mfma_f32_16x16x32_bf16 v[116:119], v[176:179], v[238:241], v[116:119]
	global_load_lds_dwordx4 v134, s[6:7]
	s_add_u32 m0, s8, 0x400
	v_mfma_f32_16x16x32_bf16 v[120:123], v[176:179], v[242:245], v[120:123]
	global_load_lds_dwordx4 v131, s[4:5]
	s_add_u32 m0, s8, 0x12400
	v_mfma_f32_16x16x32_bf16 v[124:127], v[176:179], v[246:249], v[124:127]
	global_load_lds_dwordx4 v135, s[6:7]
	s_add_u32 m0, s8, 0x800
	ds_read_b128 v[176:179], v194 offset:38912
	v_mfma_f32_16x16x32_bf16 v[0:3], v[180:183], v[204:207], v[0:3]
	global_load_lds_dwordx4 v132, s[4:5]
	s_add_u32 m0, s8, 0x12800
	v_mfma_f32_16x16x32_bf16 v[4:7], v[180:183], v[222:225], v[4:7]
	global_load_lds_dwordx4 v136, s[6:7]
	s_add_u32 m0, s8, 0xc00
	v_mfma_f32_16x16x32_bf16 v[8:11], v[180:183], v[226:229], v[8:11]
	global_load_lds_dwordx4 v133, s[4:5]
	s_add_u32 m0, s8, 0x12c00
	v_mfma_f32_16x16x32_bf16 v[12:15], v[180:183], v[230:233], v[12:15]
	global_load_lds_dwordx4 v137, s[6:7]
	v_mfma_f32_16x16x32_bf16 v[16:19], v[180:183], v[234:237], v[16:19]
	s_add_u32 s4, s4, 0x80
	s_addc_u32 s5, s5, 0
	s_add_u32 s6, s6, 0x80
	s_addc_u32 s7, s7, 0
	v_mfma_f32_16x16x32_bf16 v[20:23], v[180:183], v[238:241], v[20:23]
	v_mfma_f32_16x16x32_bf16 v[24:27], v[180:183], v[242:245], v[24:27]
	v_mfma_f32_16x16x32_bf16 v[28:31], v[180:183], v[246:249], v[28:31]
	ds_read_b128 v[180:183], v194 offset:40960
	v_mfma_f32_16x16x32_bf16 v[32:35], v[200:203], v[204:207], v[32:35]
	ds_read_b128 v[204:207], v195 offset:36864
	v_mfma_f32_16x16x32_bf16 v[36:39], v[200:203], v[222:225], v[36:39]
	ds_read_b128 v[222:225], v195 offset:38912
	v_mfma_f32_16x16x32_bf16 v[40:43], v[200:203], v[226:229], v[40:43]
	ds_read_b128 v[226:229], v195 offset:40960
	v_mfma_f32_16x16x32_bf16 v[44:47], v[200:203], v[230:233], v[44:47]
	ds_read_b128 v[230:233], v195 offset:43008
	v_mfma_f32_16x16x32_bf16 v[48:51], v[200:203], v[234:237], v[48:51]
	ds_read_b128 v[234:237], v195 offset:45056
	v_mfma_f32_16x16x32_bf16 v[52:55], v[200:203], v[238:241], v[52:55]
	ds_read_b128 v[238:241], v195 offset:47104
	v_mfma_f32_16x16x32_bf16 v[56:59], v[200:203], v[242:245], v[56:59]
	ds_read_b128 v[242:245], v195 offset:49152
	v_mfma_f32_16x16x32_bf16 v[60:63], v[200:203], v[246:249], v[60:63]
	ds_read_b128 v[246:249], v195 offset:51200
	ds_read_b128 v[200:203], v194 offset:43008
	s_waitcnt lgkmcnt(8)
; DI void lds_barrier() { asm volatile("s_waitcnt lgkmcnt(0)\n\ts_barrier" ::: "memory"); }
; #define G_LOAD(RA, RB, KT) { size_t as_ = astep, bs_ = bstep; asm volatile("" : "+s"(as_), "+s"(bs_)); \
;       _Pragma("unroll") for (int i = 0; i < 4; ++i) { RA[i] = *(const u32x4*)(Ag + i * as_ + (KT) * 64); RB[i] = *(const u32x4*)(Bg + i * bs_ + (KT) * 64); } }
; DI void gemm_run(const GemmCfg c, char* smem, float* const g_h, u16* const g_hb, float* const g_out, const int final_out) {
;     ...
;     G_LOAD(ra0, rb0, 0);
;     __syncthreads();
;     G_STORE(ra0, rb0, 0);
;     G_LOAD(ra0, rb0, 1);
;     lds_barrier();
;     int kt = 0;
;     for (; kt + 3 < nk; kt += 2) {
;       K_STEP(0, 1, kt + 2, true, true);
;       lds_barrier();
;       K_STEP(1, 0, kt + 3, true, true);
;       lds_barrier();
;     }
	v_mfma_f32_16x16x32_bf16 v[64:67], v[160:163], v[204:207], v[64:67]
	s_waitcnt lgkmcnt(7)
	v_mfma_f32_16x16x32_bf16 v[68:71], v[160:163], v[222:225], v[68:71]
	s_waitcnt lgkmcnt(6)
	v_mfma_f32_16x16x32_bf16 v[72:75], v[160:163], v[226:229], v[72:75]
	s_waitcnt lgkmcnt(5)
	v_mfma_f32_16x16x32_bf16 v[76:79], v[160:163], v[230:233], v[76:79]
	s_waitcnt lgkmcnt(4)
	v_mfma_f32_16x16x32_bf16 v[80:83], v[160:163], v[234:237], v[80:83]
	s_waitcnt lgkmcnt(3)
	v_mfma_f32_16x16x32_bf16 v[84:87], v[160:163], v[238:241], v[84:87]
	s_waitcnt lgkmcnt(2)
	v_mfma_f32_16x16x32_bf16 v[88:91], v[160:163], v[242:245], v[88:91]
	s_waitcnt lgkmcnt(1)
	v_mfma_f32_16x16x32_bf16 v[92:95], v[160:163], v[246:249], v[92:95]
	ds_read_b128 v[160:163], v215 offset:36864
	v_mfma_f32_16x16x32_bf16 v[96:99], v[176:179], v[204:207], v[96:99]
	v_mfma_f32_16x16x32_bf16 v[100:103], v[176:179], v[222:225], v[100:103]
	v_mfma_f32_16x16x32_bf16 v[104:107], v[176:179], v[226:229], v[104:107]
	v_mfma_f32_16x16x32_bf16 v[108:111], v[176:179], v[230:233], v[108:111]
	v_mfma_f32_16x16x32_bf16 v[112:115], v[176:179], v[234:237], v[112:115]
	v_mfma_f32_16x16x32_bf16 v[116:119], v[176:179], v[238:241], v[116:119]
	v_mfma_f32_16x16x32_bf16 v[120:123], v[176:179], v[242:245], v[120:123]
	v_mfma_f32_16x16x32_bf16 v[124:127], v[176:179], v[246:249], v[124:127]
	ds_read_b128 v[176:179], v215 offset:38912
	v_mfma_f32_16x16x32_bf16 v[0:3], v[180:183], v[204:207], v[0:3]
	v_mfma_f32_16x16x32_bf16 v[4:7], v[180:183], v[222:225], v[4:7]
	v_mfma_f32_16x16x32_bf16 v[8:11], v[180:183], v[226:229], v[8:11]
	v_mfma_f32_16x16x32_bf16 v[12:15], v[180:183], v[230:233], v[12:15]
	v_mfma_f32_16x16x32_bf16 v[16:19], v[180:183], v[234:237], v[16:19]
	v_mfma_f32_16x16x32_bf16 v[20:23], v[180:183], v[238:241], v[20:23]
	v_mfma_f32_16x16x32_bf16 v[24:27], v[180:183], v[242:245], v[24:27]
	v_mfma_f32_16x16x32_bf16 v[28:31], v[180:183], v[246:249], v[28:31]
	ds_read_b128 v[180:183], v215 offset:40960
	s_waitcnt lgkmcnt(3)
	v_mfma_f32_16x16x32_bf16 v[32:35], v[200:203], v[204:207], v[32:35]
	ds_read_b128 v[204:207], v197 offset:36864
	v_mfma_f32_16x16x32_bf16 v[36:39], v[200:203], v[222:225], v[36:39]
	ds_read_b128 v[222:225], v197 offset:38912
	v_mfma_f32_16x16x32_bf16 v[40:43], v[200:203], v[226:229], v[40:43]
	ds_read_b128 v[226:229], v197 offset:40960
	v_mfma_f32_16x16x32_bf16 v[44:47], v[200:203], v[230:233], v[44:47]
	ds_read_b128 v[230:233], v197 offset:43008
	v_mfma_f32_16x16x32_bf16 v[48:51], v[200:203], v[234:237], v[48:51]
	ds_read_b128 v[234:237], v197 offset:45056
	v_mfma_f32_16x16x32_bf16 v[52:55], v[200:203], v[238:241], v[52:55]
	ds_read_b128 v[238:241], v197 offset:47104
	v_mfma_f32_16x16x32_bf16 v[56:59], v[200:203], v[242:245], v[56:59]
	ds_read_b128 v[242:245], v197 offset:49152
	v_mfma_f32_16x16x32_bf16 v[60:63], v[200:203], v[246:249], v[60:63]
	ds_read_b128 v[246:249], v197 offset:51200
	ds_read_b128 v[200:203], v215 offset:43008
	s_waitcnt lgkmcnt(8)
	v_mfma_f32_16x16x32_bf16 v[64:67], v[160:163], v[204:207], v[64:67]
	s_waitcnt lgkmcnt(7)
	v_mfma_f32_16x16x32_bf16 v[68:71], v[160:163], v[222:225], v[68:71]
	s_waitcnt lgkmcnt(6)
	v_mfma_f32_16x16x32_bf16 v[72:75], v[160:163], v[226:229], v[72:75]
	s_waitcnt lgkmcnt(5)
	v_mfma_f32_16x16x32_bf16 v[76:79], v[160:163], v[230:233], v[76:79]
	s_waitcnt lgkmcnt(4)
	v_mfma_f32_16x16x32_bf16 v[80:83], v[160:163], v[234:237], v[80:83]
	s_waitcnt lgkmcnt(3)
	v_mfma_f32_16x16x32_bf16 v[84:87], v[160:163], v[238:241], v[84:87]
	s_waitcnt lgkmcnt(2)
	v_mfma_f32_16x16x32_bf16 v[88:91], v[160:163], v[242:245], v[88:91]
	s_waitcnt lgkmcnt(1)
	v_mfma_f32_16x16x32_bf16 v[92:95], v[160:163], v[246:249], v[92:95]
	s_waitcnt vmcnt(0) lgkmcnt(0)
	s_barrier
	ds_read_b128 v[160:163], v194
	v_mfma_f32_16x16x32_bf16 v[96:99], v[176:179], v[204:207], v[96:99]
	v_mfma_f32_16x16x32_bf16 v[100:103], v[176:179], v[222:225], v[100:103]
	v_mfma_f32_16x16x32_bf16 v[104:107], v[176:179], v[226:229], v[104:107]
	v_mfma_f32_16x16x32_bf16 v[108:111], v[176:179], v[230:233], v[108:111]
	s_add_u32 m0, s8, 0x9000
	v_mfma_f32_16x16x32_bf16 v[112:115], v[176:179], v[234:237], v[112:115]
	global_load_lds_dwordx4 v130, s[4:5]
	s_add_u32 m0, s8, 0x1b000
	v_mfma_f32_16x16x32_bf16 v[116:119], v[176:179], v[238:241], v[116:119]
	global_load_lds_dwordx4 v134, s[6:7]
	s_add_u32 m0, s8, 0x9400
	v_mfma_f32_16x16x32_bf16 v[120:123], v[176:179], v[242:245], v[120:123]
	global_load_lds_dwordx4 v131, s[4:5]
	s_add_u32 m0, s8, 0x1b400
	v_mfma_f32_16x16x32_bf16 v[124:127], v[176:179], v[246:249], v[124:127]
	global_load_lds_dwordx4 v135, s[6:7]
	s_add_u32 m0, s8, 0x9800
	ds_read_b128 v[176:179], v194 offset:2048
	v_mfma_f32_16x16x32_bf16 v[0:3], v[180:183], v[204:207], v[0:3]
	global_load_lds_dwordx4 v132, s[4:5]
	s_add_u32 m0, s8, 0x1b800
	v_mfma_f32_16x16x32_bf16 v[4:7], v[180:183], v[222:225], v[4:7]
	global_load_lds_dwordx4 v136, s[6:7]
	s_add_u32 m0, s8, 0x9c00
	v_mfma_f32_16x16x32_bf16 v[8:11], v[180:183], v[226:229], v[8:11]
	global_load_lds_dwordx4 v133, s[4:5]
	s_add_u32 m0, s8, 0x1bc00
	v_mfma_f32_16x16x32_bf16 v[12:15], v[180:183], v[230:233], v[12:15]
	global_load_lds_dwordx4 v137, s[6:7]
	v_mfma_f32_16x16x32_bf16 v[16:19], v[180:183], v[234:237], v[16:19]
	s_add_u32 s4, s4, 0x80
	s_addc_u32 s5, s5, 0
	s_add_u32 s6, s6, 0x80
	s_addc_u32 s7, s7, 0
	v_mfma_f32_16x16x32_bf16 v[20:23], v[180:183], v[238:241], v[20:23]
	v_mfma_f32_16x16x32_bf16 v[24:27], v[180:183], v[242:245], v[24:27]
	v_mfma_f32_16x16x32_bf16 v[28:31], v[180:183], v[246:249], v[28:31]
	ds_read_b128 v[180:183], v194 offset:4096
	v_mfma_f32_16x16x32_bf16 v[32:35], v[200:203], v[204:207], v[32:35]
	ds_read_b128 v[204:207], v195
	v_mfma_f32_16x16x32_bf16 v[36:39], v[200:203], v[222:225], v[36:39]
	ds_read_b128 v[222:225], v195 offset:2048
	v_mfma_f32_16x16x32_bf16 v[40:43], v[200:203], v[226:229], v[40:43]
	ds_read_b128 v[226:229], v195 offset:4096
	v_mfma_f32_16x16x32_bf16 v[44:47], v[200:203], v[230:233], v[44:47]
	ds_read_b128 v[230:233], v195 offset:6144
	v_mfma_f32_16x16x32_bf16 v[48:51], v[200:203], v[234:237], v[48:51]
	ds_read_b128 v[234:237], v195 offset:8192
	v_mfma_f32_16x16x32_bf16 v[52:55], v[200:203], v[238:241], v[52:55]
	ds_read_b128 v[238:241], v195 offset:10240
	v_mfma_f32_16x16x32_bf16 v[56:59], v[200:203], v[242:245], v[56:59]
	ds_read_b128 v[242:245], v195 offset:12288
	v_mfma_f32_16x16x32_bf16 v[60:63], v[200:203], v[246:249], v[60:63]
	ds_read_b128 v[246:249], v195 offset:14336
	ds_read_b128 v[200:203], v194 offset:6144
	s_add_i32 s1, s1, 2
	s_cmp_lt_i32 s1, s0
	s_cbranch_scc1 .Lgemm_kloop_nl
; DI void lds_barrier() { asm volatile("s_waitcnt lgkmcnt(0)\n\ts_barrier" ::: "memory"); }
; DI void gemm_run(const GemmCfg c, char* smem, float* const g_h, u16* const g_hb, float* const g_out, const int final_out) {
;     ...
;     for (; kt + 3 < nk; kt += 2) {
;       K_STEP(0, 1, kt + 2, true, true);
;       lds_barrier();
;       K_STEP(1, 0, kt + 3, true, true);
;       lds_barrier();
;     }
;     K_STEP(0, 1, 0, true, false);
;     lds_barrier();
;     K_STEP(1, 0, 0, false, false);
;     lds_barrier();
	s_waitcnt lgkmcnt(8)
	v_mfma_f32_16x16x32_bf16 v[64:67], v[160:163], v[204:207], v[64:67]
	s_waitcnt lgkmcnt(7)
	v_mfma_f32_16x16x32_bf16 v[68:71], v[160:163], v[222:225], v[68:71]
	s_waitcnt lgkmcnt(6)
	v_mfma_f32_16x16x32_bf16 v[72:75], v[160:163], v[226:229], v[72:75]
	s_waitcnt lgkmcnt(5)
	v_mfma_f32_16x16x32_bf16 v[76:79], v[160:163], v[230:233], v[76:79]
	s_waitcnt lgkmcnt(4)
	v_mfma_f32_16x16x32_bf16 v[80:83], v[160:163], v[234:237], v[80:83]
	s_waitcnt lgkmcnt(3)
	v_mfma_f32_16x16x32_bf16 v[84:87], v[160:163], v[238:241], v[84:87]
	s_waitcnt lgkmcnt(2)
	v_mfma_f32_16x16x32_bf16 v[88:91], v[160:163], v[242:245], v[88:91]
	s_waitcnt lgkmcnt(1)
	v_mfma_f32_16x16x32_bf16 v[92:95], v[160:163], v[246:249], v[92:95]
	ds_read_b128 v[160:163], v215
	v_mfma_f32_16x16x32_bf16 v[96:99], v[176:179], v[204:207], v[96:99]
	v_mfma_f32_16x16x32_bf16 v[100:103], v[176:179], v[222:225], v[100:103]
	v_mfma_f32_16x16x32_bf16 v[104:107], v[176:179], v[226:229], v[104:107]
	v_mfma_f32_16x16x32_bf16 v[108:111], v[176:179], v[230:233], v[108:111]
	v_mfma_f32_16x16x32_bf16 v[112:115], v[176:179], v[234:237], v[112:115]
	v_mfma_f32_16x16x32_bf16 v[116:119], v[176:179], v[238:241], v[116:119]
	v_mfma_f32_16x16x32_bf16 v[120:123], v[176:179], v[242:245], v[120:123]
	v_mfma_f32_16x16x32_bf16 v[124:127], v[176:179], v[246:249], v[124:127]
	ds_read_b128 v[176:179], v215 offset:2048
	v_mfma_f32_16x16x32_bf16 v[0:3], v[180:183], v[204:207], v[0:3]
	v_mfma_f32_16x16x32_bf16 v[4:7], v[180:183], v[222:225], v[4:7]
	v_mfma_f32_16x16x32_bf16 v[8:11], v[180:183], v[226:229], v[8:11]
	v_mfma_f32_16x16x32_bf16 v[12:15], v[180:183], v[230:233], v[12:15]
	v_mfma_f32_16x16x32_bf16 v[16:19], v[180:183], v[234:237], v[16:19]
	v_mfma_f32_16x16x32_bf16 v[20:23], v[180:183], v[238:241], v[20:23]
	v_mfma_f32_16x16x32_bf16 v[24:27], v[180:183], v[242:245], v[24:27]
	v_mfma_f32_16x16x32_bf16 v[28:31], v[180:183], v[246:249], v[28:31]
	ds_read_b128 v[180:183], v215 offset:4096
	s_waitcnt lgkmcnt(3)
	v_mfma_f32_16x16x32_bf16 v[32:35], v[200:203], v[204:207], v[32:35]
	ds_read_b128 v[204:207], v197
	v_mfma_f32_16x16x32_bf16 v[36:39], v[200:203], v[222:225], v[36:39]
	ds_read_b128 v[222:225], v197 offset:2048
	v_mfma_f32_16x16x32_bf16 v[40:43], v[200:203], v[226:229], v[40:43]
	ds_read_b128 v[226:229], v197 offset:4096
	v_mfma_f32_16x16x32_bf16 v[44:47], v[200:203], v[230:233], v[44:47]
	ds_read_b128 v[230:233], v197 offset:6144
	v_mfma_f32_16x16x32_bf16 v[48:51], v[200:203], v[234:237], v[48:51]
	ds_read_b128 v[234:237], v197 offset:8192
	v_mfma_f32_16x16x32_bf16 v[52:55], v[200:203], v[238:241], v[52:55]
	ds_read_b128 v[238:241], v197 offset:10240
	v_mfma_f32_16x16x32_bf16 v[56:59], v[200:203], v[242:245], v[56:59]
	ds_read_b128 v[242:245], v197 offset:12288
	v_mfma_f32_16x16x32_bf16 v[60:63], v[200:203], v[246:249], v[60:63]
	ds_read_b128 v[246:249], v197 offset:14336
	ds_read_b128 v[200:203], v215 offset:6144
	s_waitcnt lgkmcnt(8)
	v_mfma_f32_16x16x32_bf16 v[64:67], v[160:163], v[204:207], v[64:67]
	s_waitcnt lgkmcnt(7)
	v_mfma_f32_16x16x32_bf16 v[68:71], v[160:163], v[222:225], v[68:71]
	s_waitcnt lgkmcnt(6)
	v_mfma_f32_16x16x32_bf16 v[72:75], v[160:163], v[226:229], v[72:75]
	s_waitcnt lgkmcnt(5)
	v_mfma_f32_16x16x32_bf16 v[76:79], v[160:163], v[230:233], v[76:79]
	s_waitcnt lgkmcnt(4)
	v_mfma_f32_16x16x32_bf16 v[80:83], v[160:163], v[234:237], v[80:83]
	s_waitcnt lgkmcnt(3)
	v_mfma_f32_16x16x32_bf16 v[84:87], v[160:163], v[238:241], v[84:87]
	s_waitcnt lgkmcnt(2)
	v_mfma_f32_16x16x32_bf16 v[88:91], v[160:163], v[242:245], v[88:91]
	s_waitcnt lgkmcnt(1)
	v_mfma_f32_16x16x32_bf16 v[92:95], v[160:163], v[246:249], v[92:95]
	s_waitcnt vmcnt(0) lgkmcnt(0)
	s_barrier
	ds_read_b128 v[160:163], v194 offset:36864
	v_mfma_f32_16x16x32_bf16 v[96:99], v[176:179], v[204:207], v[96:99]
	v_mfma_f32_16x16x32_bf16 v[100:103], v[176:179], v[222:225], v[100:103]
	v_mfma_f32_16x16x32_bf16 v[104:107], v[176:179], v[226:229], v[104:107]
	v_mfma_f32_16x16x32_bf16 v[108:111], v[176:179], v[230:233], v[108:111]
	v_mfma_f32_16x16x32_bf16 v[112:115], v[176:179], v[234:237], v[112:115]
	v_mfma_f32_16x16x32_bf16 v[116:119], v[176:179], v[238:241], v[116:119]
	v_mfma_f32_16x16x32_bf16 v[120:123], v[176:179], v[242:245], v[120:123]
	v_mfma_f32_16x16x32_bf16 v[124:127], v[176:179], v[246:249], v[124:127]
	ds_read_b128 v[176:179], v194 offset:38912
	v_mfma_f32_16x16x32_bf16 v[0:3], v[180:183], v[204:207], v[0:3]
	v_mfma_f32_16x16x32_bf16 v[4:7], v[180:183], v[222:225], v[4:7]
	v_mfma_f32_16x16x32_bf16 v[8:11], v[180:183], v[226:229], v[8:11]
	v_mfma_f32_16x16x32_bf16 v[12:15], v[180:183], v[230:233], v[12:15]
	v_mfma_f32_16x16x32_bf16 v[16:19], v[180:183], v[234:237], v[16:19]
	v_mfma_f32_16x16x32_bf16 v[20:23], v[180:183], v[238:241], v[20:23]
	v_mfma_f32_16x16x32_bf16 v[24:27], v[180:183], v[242:245], v[24:27]
	v_mfma_f32_16x16x32_bf16 v[28:31], v[180:183], v[246:249], v[28:31]
	ds_read_b128 v[180:183], v194 offset:40960
	v_mfma_f32_16x16x32_bf16 v[32:35], v[200:203], v[204:207], v[32:35]
	ds_read_b128 v[204:207], v195 offset:36864
	v_mfma_f32_16x16x32_bf16 v[36:39], v[200:203], v[222:225], v[36:39]
	ds_read_b128 v[222:225], v195 offset:38912
	v_mfma_f32_16x16x32_bf16 v[40:43], v[200:203], v[226:229], v[40:43]
	ds_read_b128 v[226:229], v195 offset:40960
	v_mfma_f32_16x16x32_bf16 v[44:47], v[200:203], v[230:233], v[44:47]
	ds_read_b128 v[230:233], v195 offset:43008
	v_mfma_f32_16x16x32_bf16 v[48:51], v[200:203], v[234:237], v[48:51]
	ds_read_b128 v[234:237], v195 offset:45056
	v_mfma_f32_16x16x32_bf16 v[52:55], v[200:203], v[238:241], v[52:55]
	ds_read_b128 v[238:241], v195 offset:47104
	v_mfma_f32_16x16x32_bf16 v[56:59], v[200:203], v[242:245], v[56:59]
	ds_read_b128 v[242:245], v195 offset:49152
	v_mfma_f32_16x16x32_bf16 v[60:63], v[200:203], v[246:249], v[60:63]
	ds_read_b128 v[246:249], v195 offset:51200
	ds_read_b128 v[200:203], v194 offset:43008
	s_waitcnt lgkmcnt(8)
; DI void lds_barrier() { asm volatile("s_waitcnt lgkmcnt(0)\n\ts_barrier" ::: "memory"); }
; DI void gemm_run(const GemmCfg c, char* smem, float* const g_h, u16* const g_hb, float* const g_out, const int final_out) {
;     ...
;     K_STEP(0, 1, 0, true, false);
;     lds_barrier();
;     K_STEP(1, 0, 0, false, false);
;     lds_barrier();
	v_mfma_f32_16x16x32_bf16 v[64:67], v[160:163], v[204:207], v[64:67]
	s_waitcnt lgkmcnt(7)
	v_mfma_f32_16x16x32_bf16 v[68:71], v[160:163], v[222:225], v[68:71]
	s_waitcnt lgkmcnt(6)
	v_mfma_f32_16x16x32_bf16 v[72:75], v[160:163], v[226:229], v[72:75]
	s_waitcnt lgkmcnt(5)
	v_mfma_f32_16x16x32_bf16 v[76:79], v[160:163], v[230:233], v[76:79]
	s_waitcnt lgkmcnt(4)
	v_mfma_f32_16x16x32_bf16 v[80:83], v[160:163], v[234:237], v[80:83]
	s_waitcnt lgkmcnt(3)
	v_mfma_f32_16x16x32_bf16 v[84:87], v[160:163], v[238:241], v[84:87]
	s_waitcnt lgkmcnt(2)
	v_mfma_f32_16x16x32_bf16 v[88:91], v[160:163], v[242:245], v[88:91]
	s_waitcnt lgkmcnt(1)
	v_mfma_f32_16x16x32_bf16 v[92:95], v[160:163], v[246:249], v[92:95]
	ds_read_b128 v[160:163], v215 offset:36864
	v_mfma_f32_16x16x32_bf16 v[96:99], v[176:179], v[204:207], v[96:99]
	v_mfma_f32_16x16x32_bf16 v[100:103], v[176:179], v[222:225], v[100:103]
	v_mfma_f32_16x16x32_bf16 v[104:107], v[176:179], v[226:229], v[104:107]
	v_mfma_f32_16x16x32_bf16 v[108:111], v[176:179], v[230:233], v[108:111]
	v_mfma_f32_16x16x32_bf16 v[112:115], v[176:179], v[234:237], v[112:115]
	v_mfma_f32_16x16x32_bf16 v[116:119], v[176:179], v[238:241], v[116:119]
	v_mfma_f32_16x16x32_bf16 v[120:123], v[176:179], v[242:245], v[120:123]
	v_mfma_f32_16x16x32_bf16 v[124:127], v[176:179], v[246:249], v[124:127]
	ds_read_b128 v[176:179], v215 offset:38912
	v_mfma_f32_16x16x32_bf16 v[0:3], v[180:183], v[204:207], v[0:3]
	v_mfma_f32_16x16x32_bf16 v[4:7], v[180:183], v[222:225], v[4:7]
	v_mfma_f32_16x16x32_bf16 v[8:11], v[180:183], v[226:229], v[8:11]
	v_mfma_f32_16x16x32_bf16 v[12:15], v[180:183], v[230:233], v[12:15]
	v_mfma_f32_16x16x32_bf16 v[16:19], v[180:183], v[234:237], v[16:19]
	v_mfma_f32_16x16x32_bf16 v[20:23], v[180:183], v[238:241], v[20:23]
	v_mfma_f32_16x16x32_bf16 v[24:27], v[180:183], v[242:245], v[24:27]
	v_mfma_f32_16x16x32_bf16 v[28:31], v[180:183], v[246:249], v[28:31]
	ds_read_b128 v[180:183], v215 offset:40960
	s_waitcnt lgkmcnt(3)
	v_mfma_f32_16x16x32_bf16 v[32:35], v[200:203], v[204:207], v[32:35]
	ds_read_b128 v[204:207], v197 offset:36864
	v_mfma_f32_16x16x32_bf16 v[36:39], v[200:203], v[222:225], v[36:39]
	ds_read_b128 v[222:225], v197 offset:38912
	v_mfma_f32_16x16x32_bf16 v[40:43], v[200:203], v[226:229], v[40:43]
	ds_read_b128 v[226:229], v197 offset:40960
	v_mfma_f32_16x16x32_bf16 v[44:47], v[200:203], v[230:233], v[44:47]
	ds_read_b128 v[230:233], v197 offset:43008
	v_mfma_f32_16x16x32_bf16 v[48:51], v[200:203], v[234:237], v[48:51]
	ds_read_b128 v[234:237], v197 offset:45056
	v_mfma_f32_16x16x32_bf16 v[52:55], v[200:203], v[238:241], v[52:55]
	ds_read_b128 v[238:241], v197 offset:47104
	v_mfma_f32_16x16x32_bf16 v[56:59], v[200:203], v[242:245], v[56:59]
	ds_read_b128 v[242:245], v197 offset:49152
	v_mfma_f32_16x16x32_bf16 v[60:63], v[200:203], v[246:249], v[60:63]
	ds_read_b128 v[246:249], v197 offset:51200
	ds_read_b128 v[200:203], v215 offset:43008
	s_waitcnt lgkmcnt(8)
	v_mfma_f32_16x16x32_bf16 v[64:67], v[160:163], v[204:207], v[64:67]
	s_waitcnt lgkmcnt(7)
	v_mfma_f32_16x16x32_bf16 v[68:71], v[160:163], v[222:225], v[68:71]
	s_waitcnt lgkmcnt(6)
	v_mfma_f32_16x16x32_bf16 v[72:75], v[160:163], v[226:229], v[72:75]
	s_waitcnt lgkmcnt(5)
	v_mfma_f32_16x16x32_bf16 v[76:79], v[160:163], v[230:233], v[76:79]
	s_waitcnt lgkmcnt(4)
	v_mfma_f32_16x16x32_bf16 v[80:83], v[160:163], v[234:237], v[80:83]
	s_waitcnt lgkmcnt(3)
	v_mfma_f32_16x16x32_bf16 v[84:87], v[160:163], v[238:241], v[84:87]
	s_waitcnt lgkmcnt(2)
	v_mfma_f32_16x16x32_bf16 v[88:91], v[160:163], v[242:245], v[88:91]
	s_waitcnt lgkmcnt(1)
	v_mfma_f32_16x16x32_bf16 v[92:95], v[160:163], v[246:249], v[92:95]
	v_mfma_f32_16x16x32_bf16 v[96:99], v[176:179], v[204:207], v[96:99]
	v_mfma_f32_16x16x32_bf16 v[100:103], v[176:179], v[222:225], v[100:103]
	v_mfma_f32_16x16x32_bf16 v[104:107], v[176:179], v[226:229], v[104:107]
	v_mfma_f32_16x16x32_bf16 v[108:111], v[176:179], v[230:233], v[108:111]
	v_mfma_f32_16x16x32_bf16 v[112:115], v[176:179], v[234:237], v[112:115]
	v_mfma_f32_16x16x32_bf16 v[116:119], v[176:179], v[238:241], v[116:119]
	v_mfma_f32_16x16x32_bf16 v[120:123], v[176:179], v[242:245], v[120:123]
	v_mfma_f32_16x16x32_bf16 v[124:127], v[176:179], v[246:249], v[124:127]
	v_mfma_f32_16x16x32_bf16 v[0:3], v[180:183], v[204:207], v[0:3]
	v_mfma_f32_16x16x32_bf16 v[4:7], v[180:183], v[222:225], v[4:7]
	v_mfma_f32_16x16x32_bf16 v[8:11], v[180:183], v[226:229], v[8:11]
	v_mfma_f32_16x16x32_bf16 v[12:15], v[180:183], v[230:233], v[12:15]
	v_mfma_f32_16x16x32_bf16 v[16:19], v[180:183], v[234:237], v[16:19]
	v_mfma_f32_16x16x32_bf16 v[20:23], v[180:183], v[238:241], v[20:23]
	v_mfma_f32_16x16x32_bf16 v[24:27], v[180:183], v[242:245], v[24:27]
	v_mfma_f32_16x16x32_bf16 v[28:31], v[180:183], v[246:249], v[28:31]
	s_waitcnt lgkmcnt(0)
	v_mfma_f32_16x16x32_bf16 v[32:35], v[200:203], v[204:207], v[32:35]
	v_mfma_f32_16x16x32_bf16 v[36:39], v[200:203], v[222:225], v[36:39]
	v_mfma_f32_16x16x32_bf16 v[40:43], v[200:203], v[226:229], v[40:43]
	v_mfma_f32_16x16x32_bf16 v[44:47], v[200:203], v[230:233], v[44:47]
	v_mfma_f32_16x16x32_bf16 v[48:51], v[200:203], v[234:237], v[48:51]
	v_mfma_f32_16x16x32_bf16 v[52:55], v[200:203], v[238:241], v[52:55]
	v_mfma_f32_16x16x32_bf16 v[56:59], v[200:203], v[242:245], v[56:59]
	v_mfma_f32_16x16x32_bf16 v[60:63], v[200:203], v[246:249], v[60:63]
	s_branch .Lgemm_kdone
